# online softmax (MLA, DSA, diff): running max kept unless the tile max exceeds it by more than 8 (log2 units; exact by shift invariance, f32), so the O/l rescale branch is skipped on most tiles
# speedup vs baseline: 1.0148x; 1.0148x over previous
; __device__ __forceinline__ unsigned cvtpk(float lo, float hi) { unsigned r; asm("v_cvt_pk_bf16_f32 %0, %1, %2" : "=v"(r) : "v"(lo), "v"(hi)); return r; }
; __device__ __forceinline__ float max_x32(float v) { const unsigned u = __float_as_uint(v); auto r = __builtin_amdgcn_permlane32_swap(u, u, false, false); return fmaxf(__uint_as_float(r[0]), __uint_as_float(r[1])); }
; template <bool MASKED>
; __device__ __forceinline__ void softmax_tile(f32x16& s0, f32x16& s1, float& m, float& l, float& alpha, unsigned mlo, unsigned mhi, bf16x8 (&pk)[4]) {
;     ...
;     float mx = fmaxf(s0[0], s1[0]);
; #pragma unroll
;     for (int r = 1; r < 16; ++r) mx = fmaxf(mx, fmaxf(s0[r], s1[r]));
;     mx = max_x32(mx);
;     const float mn = fmaxf(m, mx);
;     alpha = __builtin_amdgcn_exp2f(m - mn); m = mn;
;     float sum = 0.f;
; #pragma unroll
;     for (int r = 0; r < 16; ++r) {
;         float p0 = __builtin_amdgcn_exp2f(s0[r] - mn), p1 = __builtin_amdgcn_exp2f(s1[r] - mn);
;         if (MASKED) { if (s0[r] <= -1e29f) p0 = 0.f; if (s1[r] <= -1e29f) p1 = 0.f; }
;         s0[r] = p0; s1[r] = p1; sum += p0 + p1;
;     }
;     l = l * alpha + sum;
; #pragma unroll
;     for (int k2 = 0; k2 < 2; ++k2) {
;         u32x4 a, b;
;         a.x = cvtpk(s0[8 * k2 + 0], s0[8 * k2 + 1]); a.y = cvtpk(s0[8 * k2 + 2], s0[8 * k2 + 3]); a.z = cvtpk(s0[8 * k2 + 4], s0[8 * k2 + 5]); a.w = cvtpk(s0[8 * k2 + 6], s0[8 * k2 + 7]);
;         b.x = cvtpk(s1[8 * k2 + 0], s1[8 * k2 + 1]); b.y = cvtpk(s1[8 * k2 + 2], s1[8 * k2 + 3]); b.z = cvtpk(s1[8 * k2 + 4], s1[8 * k2 + 5]); b.w = cvtpk(s1[8 * k2 + 6], s1[8 * k2 + 7]);
;         pk[k2] = __builtin_bit_cast(bf16x8, a); pk[2 + k2] = __builtin_bit_cast(bf16x8, b);
;     }
.LBB0_626:
	s_cmp_gt_i32 s7, s25
	s_cbranch_scc1 .LBB0_630
	s_mul_i32 s26, s17, 0xa000
	s_add_i32 s26, s26, 0
	v_add_u32_e32 v0, s26, v124
	v_add_u32_e32 v70, v0, v126
	v_add_u32_e32 v74, v0, v127
	ds_read_b128 v[66:69], v70
	ds_read_b128 v[70:73], v70 offset:8192
	ds_read_b128 v[150:153], v74
	ds_read_b128 v[154:157], v74 offset:8192
	v_add_u32_e32 v74, v0, v128
	v_add_u32_e32 v0, v0, v129
	ds_read_b128 v[158:161], v74
	ds_read_b128 v[162:165], v74 offset:8192
	ds_read_b128 v[166:169], v0
	ds_read_b128 v[170:173], v0 offset:8192
	s_waitcnt lgkmcnt(0)
	v_mfma_f32_32x32x16_bf16 v[82:97], v[66:69], v[98:101], 0
	v_mfma_f32_32x32x16_bf16 v[66:81], v[70:73], v[98:101], 0
	v_mfma_f32_32x32x16_bf16 v[82:97], v[150:153], v[102:105], v[82:97]
	v_mfma_f32_32x32x16_bf16 v[66:81], v[154:157], v[102:105], v[66:81]
	v_mfma_f32_32x32x16_bf16 v[82:97], v[158:161], v[106:109], v[82:97]
	v_mfma_f32_32x32x16_bf16 v[66:81], v[162:165], v[106:109], v[66:81]
	v_mfma_f32_32x32x16_bf16 v[82:97], v[166:169], v[110:113], v[82:97]
	v_mfma_f32_32x32x16_bf16 v[66:81], v[170:173], v[110:113], v[66:81]
	s_nop 11
	v_max3_f32 v150, v82, v83, v84
	v_max3_f32 v151, v85, v86, v87
	v_max3_f32 v152, v88, v89, v90
	v_max3_f32 v153, v91, v92, v93
	v_max3_f32 v154, v94, v95, v96
	v_max3_f32 v155, v97, v66, v67
	v_max3_f32 v156, v68, v69, v70
	v_max3_f32 v157, v71, v72, v73
	v_max3_f32 v158, v74, v75, v76
	v_max3_f32 v159, v77, v78, v79
	v_max3_f32 v150, v150, v151, v152
	v_max3_f32 v153, v153, v154, v155
	v_max3_f32 v156, v156, v157, v158
	v_max3_f32 v159, v159, v80, v81
	v_max3_f32 v150, v150, v153, v156
	v_max_f32_e32 v150, v150, v159
	v_mov_b32_e32 v151, v150
	s_nop 1
	v_permlane32_swap_b32_e32 v150, v151
	v_max3_f32 v146, v148, v150, v151
	v_sub_f32_e32 v150, v146, v148
	v_cmp_lt_f32_e32 vcc, 8.0, v150
	s_nop 1
	v_cndmask_b32_e32 v146, v148, v146, vcc
	v_sub_f32_e32 v0, v148, v146
	v_sub_f32_e32 v82, v82, v146
	v_sub_f32_e32 v83, v83, v146
	v_sub_f32_e32 v84, v84, v146
	v_sub_f32_e32 v85, v85, v146
	v_sub_f32_e32 v86, v86, v146
	v_sub_f32_e32 v87, v87, v146
	v_sub_f32_e32 v88, v88, v146
	v_sub_f32_e32 v89, v89, v146
	v_sub_f32_e32 v90, v90, v146
	v_sub_f32_e32 v91, v91, v146
	v_sub_f32_e32 v92, v92, v146
	v_sub_f32_e32 v93, v93, v146
	v_sub_f32_e32 v94, v94, v146
	v_sub_f32_e32 v95, v95, v146
	v_sub_f32_e32 v96, v96, v146
	v_sub_f32_e32 v97, v97, v146
	v_sub_f32_e32 v66, v66, v146
	v_sub_f32_e32 v67, v67, v146
	v_sub_f32_e32 v68, v68, v146
	v_sub_f32_e32 v69, v69, v146
	v_sub_f32_e32 v70, v70, v146
	v_sub_f32_e32 v71, v71, v146
	v_sub_f32_e32 v72, v72, v146
	v_sub_f32_e32 v73, v73, v146
	v_sub_f32_e32 v74, v74, v146
	v_sub_f32_e32 v75, v75, v146
	v_sub_f32_e32 v76, v76, v146
	v_sub_f32_e32 v77, v77, v146
	v_sub_f32_e32 v78, v78, v146
	v_sub_f32_e32 v79, v79, v146
	v_sub_f32_e32 v80, v80, v146
	v_sub_f32_e32 v81, v81, v146
	v_exp_f32_e32 v0, v0
	v_exp_f32_e32 v82, v82
	v_exp_f32_e32 v83, v83
	v_exp_f32_e32 v84, v84
	v_exp_f32_e32 v85, v85
	v_exp_f32_e32 v86, v86
	v_exp_f32_e32 v87, v87
	v_exp_f32_e32 v88, v88
	v_exp_f32_e32 v89, v89
	v_exp_f32_e32 v90, v90
	v_exp_f32_e32 v91, v91
	v_exp_f32_e32 v92, v92
	v_exp_f32_e32 v93, v93
	v_exp_f32_e32 v94, v94
	v_exp_f32_e32 v95, v95
	v_exp_f32_e32 v96, v96
	v_exp_f32_e32 v97, v97
	v_exp_f32_e32 v66, v66
	v_exp_f32_e32 v67, v67
	v_exp_f32_e32 v68, v68
	v_exp_f32_e32 v69, v69
	v_exp_f32_e32 v70, v70
	v_exp_f32_e32 v71, v71
	v_exp_f32_e32 v72, v72
	v_exp_f32_e32 v73, v73
	v_exp_f32_e32 v74, v74
	v_exp_f32_e32 v75, v75
	v_exp_f32_e32 v76, v76
	v_exp_f32_e32 v77, v77
	v_exp_f32_e32 v78, v78
	v_exp_f32_e32 v79, v79
	v_exp_f32_e32 v80, v80
	v_exp_f32_e32 v81, v81
	v_pk_add_f32 v[150:151], v[82:83], v[84:85]
	v_pk_add_f32 v[152:153], v[86:87], v[88:89]
	v_pk_add_f32 v[154:155], v[90:91], v[92:93]
	v_pk_add_f32 v[156:157], v[94:95], v[96:97]
	v_pk_add_f32 v[158:159], v[66:67], v[68:69]
	v_pk_add_f32 v[160:161], v[70:71], v[72:73]
	v_pk_add_f32 v[162:163], v[74:75], v[76:77]
	v_pk_add_f32 v[164:165], v[78:79], v[80:81]
	v_pk_add_f32 v[150:151], v[150:151], v[152:153]
	v_pk_add_f32 v[154:155], v[154:155], v[156:157]
	v_pk_add_f32 v[158:159], v[158:159], v[160:161]
	v_pk_add_f32 v[162:163], v[162:163], v[164:165]
	v_pk_add_f32 v[150:151], v[150:151], v[154:155]
	v_pk_add_f32 v[158:159], v[158:159], v[162:163]
	v_pk_add_f32 v[150:151], v[150:151], v[158:159]
	v_add_f32_e32 v164, v150, v151
	v_cvt_pk_bf16_f32 v66, v66, v67
	v_cvt_pk_bf16_f32 v67, v68, v69
	v_cvt_pk_bf16_f32 v68, v70, v71
	v_cvt_pk_bf16_f32 v69, v72, v73
	v_cvt_pk_bf16_f32 v70, v74, v75
	v_cvt_pk_bf16_f32 v71, v76, v77
	v_cvt_pk_bf16_f32 v72, v78, v79
	v_cvt_pk_bf16_f32 v73, v80, v81
	v_cvt_pk_bf16_f32 v74, v82, v83
	v_cvt_pk_bf16_f32 v75, v84, v85
	v_cvt_pk_bf16_f32 v76, v86, v87
	v_cvt_pk_bf16_f32 v77, v88, v89
	v_cvt_pk_bf16_f32 v78, v90, v91
	v_cvt_pk_bf16_f32 v79, v92, v93
	v_cvt_pk_bf16_f32 v80, v94, v95
	v_cvt_pk_bf16_f32 v81, v96, v97
	v_fmac_f32_e32 v164, v147, v0
	v_cmp_neq_f32_e32 vcc, 1.0, v0
	s_cbranch_vccz .LBB0_629
	v_pk_mul_f32 v[64:65], v[64:65], v[0:1] op_sel_hi:[1,0]
	v_pk_mul_f32 v[62:63], v[62:63], v[0:1] op_sel_hi:[1,0]
	v_pk_mul_f32 v[60:61], v[60:61], v[0:1] op_sel_hi:[1,0]
	v_pk_mul_f32 v[58:59], v[58:59], v[0:1] op_sel_hi:[1,0]
	v_pk_mul_f32 v[56:57], v[56:57], v[0:1] op_sel_hi:[1,0]
	v_pk_mul_f32 v[54:55], v[54:55], v[0:1] op_sel_hi:[1,0]
	v_pk_mul_f32 v[52:53], v[52:53], v[0:1] op_sel_hi:[1,0]
	v_pk_mul_f32 v[50:51], v[50:51], v[0:1] op_sel_hi:[1,0]
	v_pk_mul_f32 v[48:49], v[48:49], v[0:1] op_sel_hi:[1,0]
	v_pk_mul_f32 v[46:47], v[46:47], v[0:1] op_sel_hi:[1,0]
	v_pk_mul_f32 v[44:45], v[44:45], v[0:1] op_sel_hi:[1,0]
	v_pk_mul_f32 v[42:43], v[42:43], v[0:1] op_sel_hi:[1,0]
	v_pk_mul_f32 v[40:41], v[40:41], v[0:1] op_sel_hi:[1,0]
	v_pk_mul_f32 v[38:39], v[38:39], v[0:1] op_sel_hi:[1,0]
	v_pk_mul_f32 v[36:37], v[36:37], v[0:1] op_sel_hi:[1,0]
	v_pk_mul_f32 v[34:35], v[34:35], v[0:1] op_sel_hi:[1,0]
	v_pk_mul_f32 v[32:33], v[32:33], v[0:1] op_sel_hi:[1,0]
	v_pk_mul_f32 v[30:31], v[30:31], v[0:1] op_sel_hi:[1,0]
	v_pk_mul_f32 v[28:29], v[28:29], v[0:1] op_sel_hi:[1,0]
	v_pk_mul_f32 v[26:27], v[26:27], v[0:1] op_sel_hi:[1,0]
	v_pk_mul_f32 v[24:25], v[24:25], v[0:1] op_sel_hi:[1,0]
	v_pk_mul_f32 v[22:23], v[22:23], v[0:1] op_sel_hi:[1,0]
	v_pk_mul_f32 v[20:21], v[20:21], v[0:1] op_sel_hi:[1,0]
	v_pk_mul_f32 v[18:19], v[18:19], v[0:1] op_sel_hi:[1,0]
	v_pk_mul_f32 v[16:17], v[16:17], v[0:1] op_sel_hi:[1,0]
	v_pk_mul_f32 v[14:15], v[14:15], v[0:1] op_sel_hi:[1,0]
	v_pk_mul_f32 v[12:13], v[12:13], v[0:1] op_sel_hi:[1,0]
	v_pk_mul_f32 v[10:11], v[10:11], v[0:1] op_sel_hi:[1,0]
	v_pk_mul_f32 v[8:9], v[8:9], v[0:1] op_sel_hi:[1,0]
	v_pk_mul_f32 v[6:7], v[6:7], v[0:1] op_sel_hi:[1,0]
	v_pk_mul_f32 v[4:5], v[4:5], v[0:1] op_sel_hi:[1,0]
	v_pk_mul_f32 v[2:3], v[2:3], v[0:1] op_sel_hi:[1,0]

; __device__ __forceinline__ float max_x32(float v) { const unsigned u = __float_as_uint(v); auto r = __builtin_amdgcn_permlane32_swap(u, u, false, false); return fmaxf(__uint_as_float(r[0]), __uint_as_float(r[1])); }
; template <bool MASKED>
; __device__ __forceinline__ void softmax_tile(f32x16& s0, f32x16& s1, float& m, float& l, float& alpha, unsigned mlo, unsigned mhi, bf16x8 (&pk)[4]) {
;     ...
;         for (int r = 0; r < 16; ++r) { const int bit = (r & 3) + 8 * (r >> 2); if (!((mlo >> bit) & 1u)) s0[r] = NEG; if (!((mhi >> bit) & 1u)) s1[r] = NEG; }
;     }
;     float mx = fmaxf(s0[0], s1[0]);
; #pragma unroll
;     for (int r = 1; r < 16; ++r) mx = fmaxf(mx, fmaxf(s0[r], s1[r]));
;     mx = max_x32(mx);
;     const float mn = fmaxf(m, mx);
;     alpha = __builtin_amdgcn_exp2f(m - mn); m = mn;
;     float sum = 0.f;
; #pragma unroll
;     for (int r = 0; r < 16; ++r) {
;         float p0 = __builtin_amdgcn_exp2f(s0[r] - mn), p1 = __builtin_amdgcn_exp2f(s1[r] - mn);
.LBB0_1176:
	s_andn2_b64 vcc, exec, s[12:13]
	s_cbranch_vccnz .LBB0_1180
	s_mul_i32 s12, s17, 0xa000
	s_add_i32 s12, s12, 0
	v_add_u32_e32 v194, s12, v141
	v_add_u32_e32 v70, v194, v143
	v_add_u32_e32 v74, v194, v144
	ds_read_b128 v[66:69], v70
	ds_read_b128 v[70:73], v70 offset:8192
	ds_read_b128 v[160:163], v74
	ds_read_b128 v[164:167], v74 offset:8192
	v_add_u32_e32 v74, v194, v145
	ds_read_b128 v[168:171], v74
	ds_read_b128 v[172:175], v74 offset:8192
	v_add_u32_e32 v74, v194, v146
	ds_read_b128 v[186:189], v74 offset:8192
	ds_read_b128 v[190:193], v74
	s_waitcnt lgkmcnt(0)
	v_mfma_f32_32x32x16_bf16 v[82:97], v[66:69], v[98:101], 0
	v_mfma_f32_32x32x16_bf16 v[66:81], v[70:73], v[98:101], 0
	v_mfma_f32_32x32x16_bf16 v[82:97], v[160:163], v[102:105], v[82:97]
	v_mfma_f32_32x32x16_bf16 v[66:81], v[164:167], v[102:105], v[66:81]
	v_mfma_f32_32x32x16_bf16 v[82:97], v[168:171], v[106:109], v[82:97]
	v_mfma_f32_32x32x16_bf16 v[66:81], v[172:175], v[106:109], v[66:81]
	v_mfma_f32_32x32x16_bf16 v[82:97], v[190:193], v[110:113], v[82:97]
	v_mfma_f32_32x32x16_bf16 v[66:81], v[186:189], v[110:113], v[66:81]
	v_add_u32_e32 v164, v194, v147
	v_add_u32_e32 v172, v194, v148
	v_add_u32_e32 v190, v194, v149
	v_add_u32_e32 v198, v194, v150
	ds_read_b128 v[160:163], v164
	ds_read_b128 v[164:167], v164 offset:8192
	ds_read_b128 v[168:171], v172
	ds_read_b128 v[172:175], v172 offset:8192
	ds_read_b128 v[186:189], v190
	ds_read_b128 v[190:193], v190 offset:8192
	ds_read_b128 v[194:197], v198 offset:8192
	ds_read_b128 v[206:209], v198
	s_waitcnt lgkmcnt(0)
	v_mfma_f32_32x32x16_bf16 v[82:97], v[160:163], v[114:117], v[82:97]
	v_mfma_f32_32x32x16_bf16 v[66:81], v[164:167], v[114:117], v[66:81]
	v_mfma_f32_32x32x16_bf16 v[82:97], v[168:171], v[118:121], v[82:97]
	v_mfma_f32_32x32x16_bf16 v[66:81], v[172:175], v[118:121], v[66:81]
	v_mfma_f32_32x32x16_bf16 v[82:97], v[186:189], v[122:125], v[82:97]
	v_mfma_f32_32x32x16_bf16 v[66:81], v[190:193], v[122:125], v[66:81]
	v_mfma_f32_32x32x16_bf16 v[82:97], v[206:209], v[126:129], v[82:97]
	v_mfma_f32_32x32x16_bf16 v[66:81], v[194:197], v[126:129], v[66:81]
	v_bfe_i32 v160, v185, 0, 1
	v_bfe_i32 v161, v185, 1, 1
	v_bfe_i32 v162, v185, 2, 1
	v_bfe_i32 v163, v185, 3, 1
	v_bfe_i32 v164, v185, 8, 1
	v_bfe_i32 v165, v185, 9, 1
	v_bfe_i32 v166, v185, 10, 1
	v_bfe_i32 v167, v185, 11, 1
	v_bfe_i32 v168, v185, 16, 1
	v_bfe_i32 v169, v185, 17, 1
	v_bfe_i32 v170, v185, 18, 1
	v_bfe_i32 v171, v185, 19, 1
	v_bfe_i32 v172, v185, 24, 1
	v_bfe_i32 v173, v185, 25, 1
	v_bfe_i32 v174, v185, 26, 1
	v_bfe_i32 v175, v185, 27, 1
	v_bfe_i32 v186, v0, 0, 1
	v_bfe_i32 v187, v0, 1, 1
	v_bfe_i32 v188, v0, 2, 1
	v_bfe_i32 v189, v0, 3, 1
	v_bfe_i32 v190, v0, 8, 1
	v_bfe_i32 v191, v0, 9, 1
	v_bfe_i32 v192, v0, 10, 1
	v_bfe_i32 v193, v0, 11, 1
	v_bfe_i32 v194, v0, 16, 1
	v_bfe_i32 v195, v0, 17, 1
	v_bfe_i32 v196, v0, 18, 1
	v_bfe_i32 v197, v0, 19, 1
	v_bfe_i32 v198, v0, 24, 1
	v_bfe_i32 v199, v0, 25, 1
	v_bfe_i32 v206, v0, 26, 1
	v_bfe_i32 v207, v0, 27, 1
	v_bfi_b32 v82, v160, v82, v215
	v_bfi_b32 v83, v161, v83, v215
	v_bfi_b32 v84, v162, v84, v215
	v_bfi_b32 v85, v163, v85, v215
	v_bfi_b32 v86, v164, v86, v215
	v_bfi_b32 v87, v165, v87, v215
	v_bfi_b32 v88, v166, v88, v215
	v_bfi_b32 v89, v167, v89, v215
	v_bfi_b32 v90, v168, v90, v215
	v_bfi_b32 v91, v169, v91, v215
	v_bfi_b32 v92, v170, v92, v215
	v_bfi_b32 v93, v171, v93, v215
	v_bfi_b32 v94, v172, v94, v215
	v_bfi_b32 v95, v173, v95, v215
	v_bfi_b32 v96, v174, v96, v215
	v_bfi_b32 v97, v175, v97, v215
	v_bfi_b32 v66, v186, v66, v215
	v_bfi_b32 v67, v187, v67, v215
	v_bfi_b32 v68, v188, v68, v215
	v_bfi_b32 v69, v189, v69, v215
	v_bfi_b32 v70, v190, v70, v215
	v_bfi_b32 v71, v191, v71, v215
	v_bfi_b32 v72, v192, v72, v215
	v_bfi_b32 v73, v193, v73, v215
	v_bfi_b32 v74, v194, v74, v215
	v_bfi_b32 v75, v195, v75, v215
	v_bfi_b32 v76, v196, v76, v215
	v_bfi_b32 v77, v197, v77, v215
	v_bfi_b32 v78, v198, v78, v215
	v_bfi_b32 v79, v199, v79, v215
	v_bfi_b32 v80, v206, v80, v215
	v_bfi_b32 v81, v207, v81, v215
	v_max3_f32 v160, v82, v83, v84
	v_max3_f32 v161, v85, v86, v87
	v_max3_f32 v162, v88, v89, v90
	v_max3_f32 v163, v91, v92, v93
	v_max3_f32 v164, v94, v95, v96
	v_max3_f32 v165, v97, v66, v67
	v_max3_f32 v166, v68, v69, v70
	v_max3_f32 v167, v71, v72, v73
	v_max3_f32 v168, v74, v75, v76
	v_max3_f32 v169, v77, v78, v79
	v_max3_f32 v160, v160, v161, v162
	v_max3_f32 v163, v163, v164, v165
	v_max3_f32 v166, v166, v167, v168
	v_max3_f32 v169, v169, v80, v81
	v_max3_f32 v160, v160, v163, v166
	v_max_f32_e32 v160, v160, v169
	v_mov_b32_e32 v161, v160
	s_nop 1
	v_permlane32_swap_b32_e32 v160, v161
	v_max3_f32 v162, v184, v160, v161
	v_max_f32_e32 v162, s97, v162
	v_sub_f32_e32 v163, v162, v184
	v_cmp_lt_f32_e32 vcc, 8.0, v163
	s_nop 1
	v_cndmask_b32_e32 v162, v184, v162, vcc
	v_sub_f32_e32 v0, v184, v162
	v_sub_f32_e32 v82, v82, v162
	v_sub_f32_e32 v83, v83, v162
; __device__ __forceinline__ unsigned cvtpk(float lo, float hi) { unsigned r; asm("v_cvt_pk_bf16_f32 %0, %1, %2" : "=v"(r) : "v"(lo), "v"(hi)); return r; }
; template <bool MASKED>
; __device__ __forceinline__ void softmax_tile(f32x16& s0, f32x16& s1, float& m, float& l, float& alpha, unsigned mlo, unsigned mhi, bf16x8 (&pk)[4]) {
;     ...
;     for (int r = 0; r < 16; ++r) {
;         float p0 = __builtin_amdgcn_exp2f(s0[r] - mn), p1 = __builtin_amdgcn_exp2f(s1[r] - mn);
;         if (MASKED) { if (s0[r] <= -1e29f) p0 = 0.f; if (s1[r] <= -1e29f) p1 = 0.f; }
;         s0[r] = p0; s1[r] = p1; sum += p0 + p1;
;     }
;     l = l * alpha + sum;
; #pragma unroll
;     for (int k2 = 0; k2 < 2; ++k2) {
;         u32x4 a, b;
;         a.x = cvtpk(s0[8 * k2 + 0], s0[8 * k2 + 1]); a.y = cvtpk(s0[8 * k2 + 2], s0[8 * k2 + 3]); a.z = cvtpk(s0[8 * k2 + 4], s0[8 * k2 + 5]); a.w = cvtpk(s0[8 * k2 + 6], s0[8 * k2 + 7]);
;         b.x = cvtpk(s1[8 * k2 + 0], s1[8 * k2 + 1]); b.y = cvtpk(s1[8 * k2 + 2], s1[8 * k2 + 3]); b.z = cvtpk(s1[8 * k2 + 4], s1[8 * k2 + 5]); b.w = cvtpk(s1[8 * k2 + 6], s1[8 * k2 + 7]);
;         pk[k2] = __builtin_bit_cast(bf16x8, a); pk[2 + k2] = __builtin_bit_cast(bf16x8, b);
;     }
	v_sub_f32_e32 v84, v84, v162
	v_sub_f32_e32 v85, v85, v162
	v_sub_f32_e32 v86, v86, v162
	v_sub_f32_e32 v87, v87, v162
	v_sub_f32_e32 v88, v88, v162
	v_sub_f32_e32 v89, v89, v162
	v_sub_f32_e32 v90, v90, v162
	v_sub_f32_e32 v91, v91, v162
	v_sub_f32_e32 v92, v92, v162
	v_sub_f32_e32 v93, v93, v162
	v_sub_f32_e32 v94, v94, v162
	v_sub_f32_e32 v95, v95, v162
	v_sub_f32_e32 v96, v96, v162
	v_sub_f32_e32 v97, v97, v162
	v_sub_f32_e32 v66, v66, v162
	v_sub_f32_e32 v67, v67, v162
	v_sub_f32_e32 v68, v68, v162
	v_sub_f32_e32 v69, v69, v162
	v_sub_f32_e32 v70, v70, v162
	v_sub_f32_e32 v71, v71, v162
	v_sub_f32_e32 v72, v72, v162
	v_sub_f32_e32 v73, v73, v162
	v_sub_f32_e32 v74, v74, v162
	v_sub_f32_e32 v75, v75, v162
	v_sub_f32_e32 v76, v76, v162
	v_sub_f32_e32 v77, v77, v162
	v_sub_f32_e32 v78, v78, v162
	v_sub_f32_e32 v79, v79, v162
	v_sub_f32_e32 v80, v80, v162
	v_sub_f32_e32 v81, v81, v162
	v_exp_f32_e32 v0, v0
	v_exp_f32_e32 v82, v82
	v_exp_f32_e32 v83, v83
	v_exp_f32_e32 v84, v84
	v_exp_f32_e32 v85, v85
	v_exp_f32_e32 v86, v86
	v_exp_f32_e32 v87, v87
	v_exp_f32_e32 v88, v88
	v_exp_f32_e32 v89, v89
	v_exp_f32_e32 v90, v90
	v_exp_f32_e32 v91, v91
	v_exp_f32_e32 v92, v92
	v_exp_f32_e32 v93, v93
	v_exp_f32_e32 v94, v94
	v_exp_f32_e32 v95, v95
	v_exp_f32_e32 v96, v96
	v_exp_f32_e32 v97, v97
	v_exp_f32_e32 v66, v66
	v_exp_f32_e32 v67, v67
	v_exp_f32_e32 v68, v68
	v_exp_f32_e32 v69, v69
	v_exp_f32_e32 v70, v70
	v_exp_f32_e32 v71, v71
	v_exp_f32_e32 v72, v72
	v_exp_f32_e32 v73, v73
	v_exp_f32_e32 v74, v74
	v_exp_f32_e32 v75, v75
	v_exp_f32_e32 v76, v76
	v_exp_f32_e32 v77, v77
	v_exp_f32_e32 v78, v78
	v_exp_f32_e32 v79, v79
	v_exp_f32_e32 v80, v80
	v_exp_f32_e32 v81, v81
	v_pk_add_f32 v[164:165], v[82:83], v[84:85]
	v_pk_add_f32 v[166:167], v[86:87], v[88:89]
	v_pk_add_f32 v[168:169], v[90:91], v[92:93]
	v_pk_add_f32 v[170:171], v[94:95], v[96:97]
	v_pk_add_f32 v[172:173], v[66:67], v[68:69]
	v_pk_add_f32 v[174:175], v[70:71], v[72:73]
	v_pk_add_f32 v[186:187], v[74:75], v[76:77]
	v_pk_add_f32 v[188:189], v[78:79], v[80:81]
	v_pk_add_f32 v[164:165], v[164:165], v[166:167]
	v_pk_add_f32 v[168:169], v[168:169], v[170:171]
	v_pk_add_f32 v[172:173], v[172:173], v[174:175]
	v_pk_add_f32 v[186:187], v[186:187], v[188:189]
	v_pk_add_f32 v[164:165], v[164:165], v[168:169]
	v_pk_add_f32 v[172:173], v[172:173], v[186:187]
	v_pk_add_f32 v[164:165], v[164:165], v[172:173]
	v_add_f32_e32 v164, v164, v165
	v_cvt_pk_bf16_f32 v66, v66, v67
	v_cvt_pk_bf16_f32 v67, v68, v69
	v_cvt_pk_bf16_f32 v68, v70, v71
	v_cvt_pk_bf16_f32 v69, v72, v73
	v_cvt_pk_bf16_f32 v70, v74, v75
	v_cvt_pk_bf16_f32 v71, v76, v77
	v_cvt_pk_bf16_f32 v72, v78, v79
	v_cvt_pk_bf16_f32 v73, v80, v81
	v_cvt_pk_bf16_f32 v74, v82, v83
	v_cvt_pk_bf16_f32 v75, v84, v85
	v_cvt_pk_bf16_f32 v76, v86, v87
	v_cvt_pk_bf16_f32 v77, v88, v89
	v_cvt_pk_bf16_f32 v78, v90, v91
	v_cvt_pk_bf16_f32 v79, v92, v93
	v_cvt_pk_bf16_f32 v80, v94, v95
	v_cvt_pk_bf16_f32 v81, v96, v97
	v_fmac_f32_e32 v164, v183, v0
	v_mov_b32_e32 v83, v164
	v_mov_b32_e32 v82, v162
	v_cmp_neq_f32_e32 vcc, 1.0, v0
	s_cbranch_vccz .LBB0_1179
	v_pk_mul_f32 v[64:65], v[64:65], v[0:1] op_sel_hi:[1,0]
	v_pk_mul_f32 v[62:63], v[62:63], v[0:1] op_sel_hi:[1,0]
	v_pk_mul_f32 v[60:61], v[60:61], v[0:1] op_sel_hi:[1,0]
	v_pk_mul_f32 v[58:59], v[58:59], v[0:1] op_sel_hi:[1,0]
	v_pk_mul_f32 v[56:57], v[56:57], v[0:1] op_sel_hi:[1,0]
	v_pk_mul_f32 v[54:55], v[54:55], v[0:1] op_sel_hi:[1,0]
	v_pk_mul_f32 v[52:53], v[52:53], v[0:1] op_sel_hi:[1,0]
	v_pk_mul_f32 v[50:51], v[50:51], v[0:1] op_sel_hi:[1,0]
	v_pk_mul_f32 v[48:49], v[48:49], v[0:1] op_sel_hi:[1,0]
	v_pk_mul_f32 v[46:47], v[46:47], v[0:1] op_sel_hi:[1,0]
	v_pk_mul_f32 v[44:45], v[44:45], v[0:1] op_sel_hi:[1,0]
	v_pk_mul_f32 v[42:43], v[42:43], v[0:1] op_sel_hi:[1,0]
	v_pk_mul_f32 v[40:41], v[40:41], v[0:1] op_sel_hi:[1,0]
	v_pk_mul_f32 v[38:39], v[38:39], v[0:1] op_sel_hi:[1,0]
	v_pk_mul_f32 v[36:37], v[36:37], v[0:1] op_sel_hi:[1,0]
	v_pk_mul_f32 v[34:35], v[34:35], v[0:1] op_sel_hi:[1,0]
	v_pk_mul_f32 v[32:33], v[32:33], v[0:1] op_sel_hi:[1,0]
	v_pk_mul_f32 v[30:31], v[30:31], v[0:1] op_sel_hi:[1,0]
	v_pk_mul_f32 v[28:29], v[28:29], v[0:1] op_sel_hi:[1,0]
	v_pk_mul_f32 v[26:27], v[26:27], v[0:1] op_sel_hi:[1,0]
	v_pk_mul_f32 v[24:25], v[24:25], v[0:1] op_sel_hi:[1,0]
	v_pk_mul_f32 v[22:23], v[22:23], v[0:1] op_sel_hi:[1,0]
	v_pk_mul_f32 v[20:21], v[20:21], v[0:1] op_sel_hi:[1,0]
	v_pk_mul_f32 v[18:19], v[18:19], v[0:1] op_sel_hi:[1,0]
	v_pk_mul_f32 v[16:17], v[16:17], v[0:1] op_sel_hi:[1,0]
	v_pk_mul_f32 v[14:15], v[14:15], v[0:1] op_sel_hi:[1,0]
	v_pk_mul_f32 v[12:13], v[12:13], v[0:1] op_sel_hi:[1,0]
	v_pk_mul_f32 v[10:11], v[10:11], v[0:1] op_sel_hi:[1,0]
	v_pk_mul_f32 v[8:9], v[8:9], v[0:1] op_sel_hi:[1,0]
	v_pk_mul_f32 v[6:7], v[6:7], v[0:1] op_sel_hi:[1,0]
	v_pk_mul_f32 v[4:5], v[4:5], v[0:1] op_sel_hi:[1,0]
	v_pk_mul_f32 v[2:3], v[2:3], v[0:1] op_sel_hi:[1,0]

; __device__ __forceinline__ unsigned cvtpk(float lo, float hi) { unsigned r; asm("v_cvt_pk_bf16_f32 %0, %1, %2" : "=v"(r) : "v"(lo), "v"(hi)); return r; }
; __device__ __forceinline__ float max_x32(float v) { const unsigned u = __float_as_uint(v); auto r = __builtin_amdgcn_permlane32_swap(u, u, false, false); return fmaxf(__uint_as_float(r[0]), __uint_as_float(r[1])); }
; template <bool MASKED>
; __device__ __forceinline__ void softmax_tile(f32x16& s0, f32x16& s1, float& m, float& l, float& alpha, unsigned mlo, unsigned mhi, bf16x8 (&pk)[4]) {
;     ...
;     float mx = fmaxf(s0[0], s1[0]);
; #pragma unroll
;     for (int r = 1; r < 16; ++r) mx = fmaxf(mx, fmaxf(s0[r], s1[r]));
;     mx = max_x32(mx);
;     const float mn = fmaxf(m, mx);
;     alpha = __builtin_amdgcn_exp2f(m - mn); m = mn;
;     float sum = 0.f;
; #pragma unroll
;     for (int r = 0; r < 16; ++r) {
;         float p0 = __builtin_amdgcn_exp2f(s0[r] - mn), p1 = __builtin_amdgcn_exp2f(s1[r] - mn);
;         if (MASKED) { if (s0[r] <= -1e29f) p0 = 0.f; if (s1[r] <= -1e29f) p1 = 0.f; }
;         s0[r] = p0; s1[r] = p1; sum += p0 + p1;
;     }
;     l = l * alpha + sum;
; #pragma unroll
;     for (int k2 = 0; k2 < 2; ++k2) {
;         u32x4 a, b;
;         a.x = cvtpk(s0[8 * k2 + 0], s0[8 * k2 + 1]); a.y = cvtpk(s0[8 * k2 + 2], s0[8 * k2 + 3]); a.z = cvtpk(s0[8 * k2 + 4], s0[8 * k2 + 5]); a.w = cvtpk(s0[8 * k2 + 6], s0[8 * k2 + 7]);
;         b.x = cvtpk(s1[8 * k2 + 0], s1[8 * k2 + 1]); b.y = cvtpk(s1[8 * k2 + 2], s1[8 * k2 + 3]); b.z = cvtpk(s1[8 * k2 + 4], s1[8 * k2 + 5]); b.w = cvtpk(s1[8 * k2 + 6], s1[8 * k2 + 7]);
;         pk[k2] = __builtin_bit_cast(bf16x8, a); pk[2 + k2] = __builtin_bit_cast(bf16x8, b);
;     }
.LBB0_1190:
	s_cmp_gt_i32 s14, s49
	s_cbranch_scc1 .LBB0_1194
	s_mul_i32 s15, s50, 0xa000
	s_add_i32 s15, s15, 0
	v_add_u32_e32 v0, s15, v186
	v_add_u32_e32 v6, v0, v188
	v_add_u32_e32 v14, v0, v189
	ds_read_b128 v[2:5], v6
	ds_read_b128 v[6:9], v6 offset:8192
	ds_read_b128 v[10:13], v14
	ds_read_b128 v[160:163], v14 offset:8192
	v_add_u32_e32 v14, v0, v190
	ds_read_b128 v[164:167], v14
	ds_read_b128 v[168:171], v14 offset:8192
	v_add_u32_e32 v14, v0, v191
	ds_read_b128 v[172:175], v14 offset:8192
	ds_read_b128 v[206:209], v14
	v_add_u32_e32 v14, s15, v177
	s_waitcnt lgkmcnt(0)
	v_mfma_f32_32x32x16_bf16 v[96:111], v[2:5], v[112:115], 0
	v_mfma_f32_32x32x16_bf16 v[80:95], v[6:9], v[112:115], 0
	v_mfma_f32_32x32x16_bf16 v[96:111], v[10:13], v[116:119], v[96:111]
	v_mfma_f32_32x32x16_bf16 v[80:95], v[160:163], v[116:119], v[80:95]
	v_mfma_f32_32x32x16_bf16 v[96:111], v[164:167], v[120:123], v[96:111]
	v_mfma_f32_32x32x16_bf16 v[80:95], v[168:171], v[120:123], v[80:95]
	v_mfma_f32_32x32x16_bf16 v[96:111], v[206:209], v[124:127], v[96:111]
	v_mfma_f32_32x32x16_bf16 v[80:95], v[172:175], v[124:127], v[80:95]
	v_add_u32_e32 v6, v0, v192
	v_add_u32_e32 v15, v0, v193
	ds_read_b128 v[2:5], v6
	ds_read_b128 v[6:9], v6 offset:8192
	ds_read_b128 v[10:13], v15
	ds_read_b128 v[160:163], v15 offset:8192
	v_add_u32_e32 v15, v0, v194
	v_add_u32_e32 v0, v0, v195
	ds_read_b128 v[164:167], v15
	ds_read_b128 v[168:171], v15 offset:8192
	ds_read_b128 v[172:175], v0 offset:8192
	ds_read_b128 v[206:209], v0
	s_waitcnt lgkmcnt(0)
	v_mfma_f32_32x32x16_bf16 v[96:111], v[2:5], v[128:131], v[96:111]
	v_mfma_f32_32x32x16_bf16 v[80:95], v[6:9], v[128:131], v[80:95]
	v_mfma_f32_32x32x16_bf16 v[96:111], v[10:13], v[132:135], v[96:111]
	v_mfma_f32_32x32x16_bf16 v[80:95], v[160:163], v[132:135], v[80:95]
	v_mfma_f32_32x32x16_bf16 v[96:111], v[164:167], v[136:139], v[96:111]
	v_mfma_f32_32x32x16_bf16 v[80:95], v[168:171], v[136:139], v[80:95]
	v_mfma_f32_32x32x16_bf16 v[96:111], v[206:209], v[140:143], v[96:111]
	v_mfma_f32_32x32x16_bf16 v[80:95], v[172:175], v[140:143], v[80:95]
	v_add_u32_e32 v0, v14, v196
	ds_read_b128 v[2:5], v0 offset:32768
	ds_read_b128 v[6:9], v0 offset:36864
	v_add_u32_e32 v0, v14, v197
	ds_read_b128 v[10:13], v0 offset:32768
	ds_read_b128 v[160:163], v0 offset:36864
	v_add_u32_e32 v0, v14, v198
	ds_read_b128 v[164:167], v0 offset:32768
	ds_read_b128 v[168:171], v0 offset:36864
	v_add_u32_e32 v0, v14, v199
	ds_read_b128 v[172:175], v0 offset:36864
	ds_read_b128 v[206:209], v0 offset:32768
	s_waitcnt lgkmcnt(0)
	v_mfma_f32_32x32x16_bf16 v[96:111], v[2:5], v[144:147], v[96:111]
	v_mfma_f32_32x32x16_bf16 v[80:95], v[6:9], v[144:147], v[80:95]
	v_mfma_f32_32x32x16_bf16 v[96:111], v[10:13], v[148:151], v[96:111]
	v_mfma_f32_32x32x16_bf16 v[80:95], v[160:163], v[148:151], v[80:95]
	v_mfma_f32_32x32x16_bf16 v[96:111], v[164:167], v[152:155], v[96:111]
	v_mfma_f32_32x32x16_bf16 v[80:95], v[168:171], v[152:155], v[80:95]
	v_mfma_f32_32x32x16_bf16 v[96:111], v[206:209], v[156:159], v[96:111]
	v_mfma_f32_32x32x16_bf16 v[80:95], v[172:175], v[156:159], v[80:95]
	s_nop 11
	v_max3_f32 v160, v96, v97, v98
	v_max3_f32 v161, v99, v100, v101
	v_max3_f32 v162, v102, v103, v104
	v_max3_f32 v163, v105, v106, v107
	v_max3_f32 v164, v108, v109, v110
	v_max3_f32 v165, v111, v80, v81
	v_max3_f32 v166, v82, v83, v84
	v_max3_f32 v167, v85, v86, v87
	v_max3_f32 v168, v88, v89, v90
	v_max3_f32 v169, v91, v92, v93
	v_max3_f32 v160, v160, v161, v162
	v_max3_f32 v163, v163, v164, v165
	v_max3_f32 v166, v166, v167, v168
	v_max3_f32 v169, v169, v94, v95
	v_max3_f32 v160, v160, v163, v166
	v_max_f32_e32 v160, v160, v169
	v_mov_b32_e32 v161, v160
	s_nop 1
	v_permlane32_swap_b32_e32 v160, v161
	v_max3_f32 v14, v235, v160, v161
	v_sub_f32_e32 v160, v14, v235
	v_cmp_lt_f32_e32 vcc, 8.0, v160
	s_nop 1
	v_cndmask_b32_e32 v14, v235, v14, vcc
	v_sub_f32_e32 v0, v235, v14
	v_sub_f32_e32 v96, v96, v14
	v_sub_f32_e32 v97, v97, v14
	v_sub_f32_e32 v98, v98, v14
	v_sub_f32_e32 v99, v99, v14
	v_sub_f32_e32 v100, v100, v14
	v_sub_f32_e32 v101, v101, v14
	v_sub_f32_e32 v102, v102, v14
	v_sub_f32_e32 v103, v103, v14
	v_sub_f32_e32 v104, v104, v14
	v_sub_f32_e32 v105, v105, v14
	v_sub_f32_e32 v106, v106, v14
	v_sub_f32_e32 v107, v107, v14
	v_sub_f32_e32 v108, v108, v14
	v_sub_f32_e32 v109, v109, v14
	v_sub_f32_e32 v110, v110, v14
	v_sub_f32_e32 v111, v111, v14
	v_sub_f32_e32 v80, v80, v14
	v_sub_f32_e32 v81, v81, v14
	v_sub_f32_e32 v82, v82, v14
	v_sub_f32_e32 v83, v83, v14
	v_sub_f32_e32 v84, v84, v14
	v_sub_f32_e32 v85, v85, v14
	v_sub_f32_e32 v86, v86, v14
	v_sub_f32_e32 v87, v87, v14
	v_sub_f32_e32 v88, v88, v14
	v_sub_f32_e32 v89, v89, v14
	v_sub_f32_e32 v90, v90, v14
	v_sub_f32_e32 v91, v91, v14
	v_sub_f32_e32 v92, v92, v14
	v_sub_f32_e32 v93, v93, v14
	v_sub_f32_e32 v94, v94, v14
	v_sub_f32_e32 v95, v95, v14
	v_exp_f32_e32 v0, v0
	v_exp_f32_e32 v96, v96
	v_exp_f32_e32 v97, v97
	v_exp_f32_e32 v98, v98
	v_exp_f32_e32 v99, v99
	v_exp_f32_e32 v100, v100
	v_exp_f32_e32 v101, v101
	v_exp_f32_e32 v102, v102
	v_exp_f32_e32 v103, v103
	v_exp_f32_e32 v104, v104
	v_exp_f32_e32 v105, v105
	v_exp_f32_e32 v106, v106
	v_exp_f32_e32 v107, v107
	v_exp_f32_e32 v108, v108
	v_exp_f32_e32 v109, v109
	v_exp_f32_e32 v110, v110
	v_exp_f32_e32 v111, v111
	v_exp_f32_e32 v80, v80
	v_exp_f32_e32 v81, v81
	v_exp_f32_e32 v82, v82
	v_exp_f32_e32 v83, v83
	v_exp_f32_e32 v84, v84
	v_exp_f32_e32 v85, v85
	v_exp_f32_e32 v86, v86
	v_exp_f32_e32 v87, v87
	v_exp_f32_e32 v88, v88
	v_exp_f32_e32 v89, v89
	v_exp_f32_e32 v90, v90
	v_exp_f32_e32 v91, v91
	v_exp_f32_e32 v92, v92
	v_exp_f32_e32 v93, v93
	v_exp_f32_e32 v94, v94
	v_exp_f32_e32 v95, v95
	v_pk_add_f32 v[160:161], v[96:97], v[98:99]
	v_pk_add_f32 v[162:163], v[100:101], v[102:103]
	v_pk_add_f32 v[164:165], v[104:105], v[106:107]
	v_pk_add_f32 v[166:167], v[108:109], v[110:111]
	v_pk_add_f32 v[168:169], v[80:81], v[82:83]
	v_pk_add_f32 v[170:171], v[84:85], v[86:87]
	v_pk_add_f32 v[172:173], v[88:89], v[90:91]
	v_pk_add_f32 v[174:175], v[92:93], v[94:95]
	v_pk_add_f32 v[160:161], v[160:161], v[162:163]
	v_pk_add_f32 v[164:165], v[164:165], v[166:167]
	v_pk_add_f32 v[168:169], v[168:169], v[170:171]
	v_pk_add_f32 v[172:173], v[172:173], v[174:175]
	v_pk_add_f32 v[160:161], v[160:161], v[164:165]
	v_pk_add_f32 v[168:169], v[168:169], v[172:173]
	v_pk_add_f32 v[160:161], v[160:161], v[168:169]
	v_add_f32_e32 v15, v160, v161
	v_cvt_pk_bf16_f32 v2, v80, v81
	v_cvt_pk_bf16_f32 v3, v82, v83
	v_cvt_pk_bf16_f32 v4, v84, v85
	v_cvt_pk_bf16_f32 v5, v86, v87
	v_cvt_pk_bf16_f32 v6, v88, v89
	v_cvt_pk_bf16_f32 v7, v90, v91
	v_cvt_pk_bf16_f32 v8, v92, v93
	v_cvt_pk_bf16_f32 v9, v94, v95
	v_cvt_pk_bf16_f32 v80, v104, v105
	v_cvt_pk_bf16_f32 v81, v106, v107
	v_cvt_pk_bf16_f32 v82, v108, v109
	v_cvt_pk_bf16_f32 v83, v110, v111
	v_cvt_pk_bf16_f32 v10, v96, v97
	v_cvt_pk_bf16_f32 v11, v98, v99
	v_cvt_pk_bf16_f32 v12, v100, v101
	v_cvt_pk_bf16_f32 v13, v102, v103
	v_fmac_f32_e32 v15, v234, v0
	v_cmp_neq_f32_e32 vcc, 1.0, v0
	s_cbranch_vccz .LBB0_1193
	v_pk_mul_f32 v[78:79], v[78:79], v[0:1] op_sel_hi:[1,0]
	v_pk_mul_f32 v[76:77], v[76:77], v[0:1] op_sel_hi:[1,0]
	v_pk_mul_f32 v[74:75], v[74:75], v[0:1] op_sel_hi:[1,0]
	v_pk_mul_f32 v[72:73], v[72:73], v[0:1] op_sel_hi:[1,0]
	v_pk_mul_f32 v[70:71], v[70:71], v[0:1] op_sel_hi:[1,0]
	v_pk_mul_f32 v[68:69], v[68:69], v[0:1] op_sel_hi:[1,0]
	v_pk_mul_f32 v[66:67], v[66:67], v[0:1] op_sel_hi:[1,0]
	v_pk_mul_f32 v[64:65], v[64:65], v[0:1] op_sel_hi:[1,0]
	v_pk_mul_f32 v[62:63], v[62:63], v[0:1] op_sel_hi:[1,0]
	v_pk_mul_f32 v[60:61], v[60:61], v[0:1] op_sel_hi:[1,0]
	v_pk_mul_f32 v[58:59], v[58:59], v[0:1] op_sel_hi:[1,0]
	v_pk_mul_f32 v[56:57], v[56:57], v[0:1] op_sel_hi:[1,0]
	v_pk_mul_f32 v[54:55], v[54:55], v[0:1] op_sel_hi:[1,0]
	v_pk_mul_f32 v[52:53], v[52:53], v[0:1] op_sel_hi:[1,0]
	v_pk_mul_f32 v[50:51], v[50:51], v[0:1] op_sel_hi:[1,0]
	v_pk_mul_f32 v[48:49], v[48:49], v[0:1] op_sel_hi:[1,0]
	v_pk_mul_f32 v[46:47], v[46:47], v[0:1] op_sel_hi:[1,0]
	v_pk_mul_f32 v[44:45], v[44:45], v[0:1] op_sel_hi:[1,0]
	v_pk_mul_f32 v[42:43], v[42:43], v[0:1] op_sel_hi:[1,0]
	v_pk_mul_f32 v[40:41], v[40:41], v[0:1] op_sel_hi:[1,0]
	v_pk_mul_f32 v[38:39], v[38:39], v[0:1] op_sel_hi:[1,0]
	v_pk_mul_f32 v[36:37], v[36:37], v[0:1] op_sel_hi:[1,0]
	v_pk_mul_f32 v[34:35], v[34:35], v[0:1] op_sel_hi:[1,0]
	v_pk_mul_f32 v[32:33], v[32:33], v[0:1] op_sel_hi:[1,0]
	v_pk_mul_f32 v[30:31], v[30:31], v[0:1] op_sel_hi:[1,0]
	v_pk_mul_f32 v[28:29], v[28:29], v[0:1] op_sel_hi:[1,0]
	v_pk_mul_f32 v[26:27], v[26:27], v[0:1] op_sel_hi:[1,0]
	v_pk_mul_f32 v[24:25], v[24:25], v[0:1] op_sel_hi:[1,0]
	v_pk_mul_f32 v[22:23], v[22:23], v[0:1] op_sel_hi:[1,0]
	v_pk_mul_f32 v[20:21], v[20:21], v[0:1] op_sel_hi:[1,0]
	v_pk_mul_f32 v[18:19], v[18:19], v[0:1] op_sel_hi:[1,0]
	v_pk_mul_f32 v[16:17], v[16:17], v[0:1] op_sel_hi:[1,0]
